# v21: v16 + P1 q/k/gate_B epilogue without the 8 accumulator copies per store group (no-activation tiles convert straight from the accumulators in an out-of-line block)
# speedup vs baseline: 1.0183x; 1.0183x over previous
; __device__ __forceinline__ u32x4 pack8(f32x4 v0, f32x4 v1) { u32x4 w; w.x = cvt_pk_bf16(v0[0], v0[1]); w.y = cvt_pk_bf16(v0[2], v0[3]); w.z = cvt_pk_bf16(v1[0], v1[1]); w.w = cvt_pk_bf16(v1[2], v1[3]); return w; }
; __device__ __forceinline__ f32x4 sigmoid4(f32x4 v) { const f32x2 a = sigmoid2((f32x2){v[0], v[1]}), b = sigmoid2((f32x2){v[2], v[3]}); return (f32x4){a.x, a.y, b.x, b.y}; }
; __device__ __forceinline__ f32x2 sigmoid2(f32x2 x) { const f32x2 t = x * (-LOG2E); f32x2 e; e.x = __builtin_amdgcn_exp2f(t.x); e.y = __builtin_amdgcn_exp2f(t.y);
;     const f32x2 d = e + 1.0f; f32x2 r; r.x = __builtin_amdgcn_rcpf(d.x); r.y = __builtin_amdgcn_rcpf(d.y); return r; }
;     __device__ __forceinline__ void operator()(const f32x4 (&acc)[2][2][4][2], const Unit& u, int ui, int wr, int wc, int fr, int fq) const {
;     ...
;         const int r0 = row0 + wr * 64 + fr, c0 = col0 + wc * 32 + 8 * fq;
; #pragma unroll
;         for (int ai = 0; ai < 2; ++ai)
; #pragma unroll
;             for (int m = 0; m < 4; ++m) { bf16_t* rowp = base + (size_t)(r0 + ai * 128 + m * 16) * ld + c0;
; #pragma unroll
;                 for (int bj = 0; bj < 2; ++bj) { f32x4 v0 = acc[ai][bj][m][0], v1 = acc[ai][bj][m][1];
;                     if (act == 2) { v0 = sigmoid4(v0); v1 = sigmoid4(v1); }
;                     *(u32x4*)(rowp + bj * 128) = pack8(v0, v1); } }
.LBB0_137:
	v_cndmask_b32_e64 v140, 0, 1, s[82:83]
	v_cmp_ne_u32_e64 s[6:7], 1, v140
	s_andn2_b64 vcc, exec, s[82:83]
	s_cbranch_vccnz .Lp1f_0
	v_pk_mul_f32 v[150:151], v[120:121], s[60:61] op_sel_hi:[1,0]
	s_nop 0
	v_exp_f32_e32 v150, v150
	v_exp_f32_e32 v151, v151
	s_nop 0
	v_pk_add_f32 v[150:151], v[150:151], 1.0 op_sel_hi:[1,0]
	s_nop 0
	v_rcp_f32_e32 v155, v150
	v_rcp_f32_e32 v156, v151
	v_pk_mul_f32 v[150:151], v[122:123], s[60:61] op_sel_hi:[1,0]
	s_nop 0
	v_exp_f32_e32 v150, v150
	v_exp_f32_e32 v151, v151
	s_nop 0
	v_pk_add_f32 v[150:151], v[150:151], 1.0 op_sel_hi:[1,0]
	s_nop 0
	v_rcp_f32_e32 v157, v150
	v_rcp_f32_e32 v158, v151
	v_pk_mul_f32 v[150:151], v[116:117], s[60:61] op_sel_hi:[1,0]
	s_nop 0
	v_exp_f32_e32 v150, v150
	v_exp_f32_e32 v151, v151
	s_nop 0
	v_pk_add_f32 v[150:151], v[150:151], 1.0 op_sel_hi:[1,0]
	s_nop 0
	v_rcp_f32_e32 v159, v150
	v_rcp_f32_e32 v160, v151
	v_pk_mul_f32 v[150:151], v[118:119], s[60:61] op_sel_hi:[1,0]
	s_nop 0
	v_exp_f32_e32 v150, v150
	v_exp_f32_e32 v151, v151
	s_nop 0
	v_pk_add_f32 v[150:151], v[150:151], 1.0 op_sel_hi:[1,0]
	s_nop 0
	v_rcp_f32_e32 v161, v150
	v_rcp_f32_e32 v162, v151

; __device__ __forceinline__ u32x4 pack8(f32x4 v0, f32x4 v1) { u32x4 w; w.x = cvt_pk_bf16(v0[0], v0[1]); w.y = cvt_pk_bf16(v0[2], v0[3]); w.z = cvt_pk_bf16(v1[0], v1[1]); w.w = cvt_pk_bf16(v1[2], v1[3]); return w; }
; __device__ __forceinline__ f32x4 sigmoid4(f32x4 v) { const f32x2 a = sigmoid2((f32x2){v[0], v[1]}), b = sigmoid2((f32x2){v[2], v[3]}); return (f32x4){a.x, a.y, b.x, b.y}; }
; __device__ __forceinline__ f32x2 sigmoid2(f32x2 x) { const f32x2 t = x * (-LOG2E); f32x2 e; e.x = __builtin_amdgcn_exp2f(t.x); e.y = __builtin_amdgcn_exp2f(t.y);
;     const f32x2 d = e + 1.0f; f32x2 r; r.x = __builtin_amdgcn_rcpf(d.x); r.y = __builtin_amdgcn_rcpf(d.y); return r; }
;     __device__ __forceinline__ void operator()(const f32x4 (&acc)[2][2][4][2], const Unit& u, int ui, int wr, int wc, int fr, int fq) const {
;     ...
;             for (int m = 0; m < 4; ++m) { bf16_t* rowp = base + (size_t)(r0 + ai * 128 + m * 16) * ld + c0;
; #pragma unroll
;                 for (int bj = 0; bj < 2; ++bj) { f32x4 v0 = acc[ai][bj][m][0], v1 = acc[ai][bj][m][1];
;                     if (act == 2) { v0 = sigmoid4(v0); v1 = sigmoid4(v1); }
;                     *(u32x4*)(rowp + bj * 128) = pack8(v0, v1); } }
.Lp1a_0:
	s_and_b64 vcc, exec, s[6:7]
	s_cbranch_vccnz .Lp1f_1
	v_pk_mul_f32 v[156:157], v[124:125], s[60:61] op_sel_hi:[1,0]
	v_pk_mul_f32 v[158:159], v[126:127], s[60:61] op_sel_hi:[1,0]
	v_pk_mul_f32 v[160:161], v[112:113], s[60:61] op_sel_hi:[1,0]
	v_pk_mul_f32 v[162:163], v[114:115], s[60:61] op_sel_hi:[1,0]
	v_exp_f32_e32 v156, v156
	v_exp_f32_e32 v157, v157
	v_exp_f32_e32 v158, v158
	v_exp_f32_e32 v159, v159
	v_exp_f32_e32 v160, v160
	v_exp_f32_e32 v161, v161
	v_exp_f32_e32 v162, v162
	v_exp_f32_e32 v163, v163
	v_pk_add_f32 v[156:157], v[156:157], 1.0 op_sel_hi:[1,0]
	v_pk_add_f32 v[158:159], v[158:159], 1.0 op_sel_hi:[1,0]
	v_pk_add_f32 v[160:161], v[160:161], 1.0 op_sel_hi:[1,0]
	v_pk_add_f32 v[162:163], v[162:163], 1.0 op_sel_hi:[1,0]
	v_rcp_f32_e32 v155, v156
	v_rcp_f32_e32 v156, v157
	v_rcp_f32_e32 v157, v158
	v_rcp_f32_e32 v158, v159
	v_rcp_f32_e32 v159, v160
	v_rcp_f32_e32 v160, v161
	v_rcp_f32_e32 v161, v162
	v_rcp_f32_e32 v162, v163

; __device__ __forceinline__ u32x4 pack8(f32x4 v0, f32x4 v1) { u32x4 w; w.x = cvt_pk_bf16(v0[0], v0[1]); w.y = cvt_pk_bf16(v0[2], v0[3]); w.z = cvt_pk_bf16(v1[0], v1[1]); w.w = cvt_pk_bf16(v1[2], v1[3]); return w; }
; __device__ __forceinline__ f32x4 sigmoid4(f32x4 v) { const f32x2 a = sigmoid2((f32x2){v[0], v[1]}), b = sigmoid2((f32x2){v[2], v[3]}); return (f32x4){a.x, a.y, b.x, b.y}; }
; __device__ __forceinline__ f32x2 sigmoid2(f32x2 x) { const f32x2 t = x * (-LOG2E); f32x2 e; e.x = __builtin_amdgcn_exp2f(t.x); e.y = __builtin_amdgcn_exp2f(t.y);
;     const f32x2 d = e + 1.0f; f32x2 r; r.x = __builtin_amdgcn_rcpf(d.x); r.y = __builtin_amdgcn_rcpf(d.y); return r; }
;     __device__ __forceinline__ void operator()(const f32x4 (&acc)[2][2][4][2], const Unit& u, int ui, int wr, int wc, int fr, int fq) const {
;     ...
;             for (int m = 0; m < 4; ++m) { bf16_t* rowp = base + (size_t)(r0 + ai * 128 + m * 16) * ld + c0;
; #pragma unroll
;                 for (int bj = 0; bj < 2; ++bj) { f32x4 v0 = acc[ai][bj][m][0], v1 = acc[ai][bj][m][1];
;                     if (act == 2) { v0 = sigmoid4(v0); v1 = sigmoid4(v1); }
;                     *(u32x4*)(rowp + bj * 128) = pack8(v0, v1); } }
.Lp1a_1:
	s_and_b64 vcc, exec, s[6:7]
	s_cbranch_vccnz .Lp1f_2
	v_pk_mul_f32 v[152:153], v[104:105], s[60:61] op_sel_hi:[1,0]
	v_pk_mul_f32 v[156:157], v[106:107], s[60:61] op_sel_hi:[1,0]
	v_exp_f32_e32 v152, v152
	v_exp_f32_e32 v153, v153
	v_exp_f32_e32 v158, v156
	v_exp_f32_e32 v159, v157
	v_pk_mul_f32 v[160:161], v[102:103], s[60:61] op_sel_hi:[1,0]
	v_pk_add_f32 v[152:153], v[152:153], 1.0 op_sel_hi:[1,0]
	v_exp_f32_e32 v162, v160
	v_rcp_f32_e32 v155, v152
	v_rcp_f32_e32 v156, v153
	v_pk_add_f32 v[152:153], v[158:159], 1.0 op_sel_hi:[1,0]
	v_exp_f32_e32 v163, v161
	v_rcp_f32_e32 v157, v152
	v_rcp_f32_e32 v158, v153
	v_pk_mul_f32 v[152:153], v[100:101], s[60:61] op_sel_hi:[1,0]
	s_nop 0
	v_exp_f32_e32 v152, v152
	v_exp_f32_e32 v153, v153
	s_nop 0
	v_pk_add_f32 v[152:153], v[152:153], 1.0 op_sel_hi:[1,0]
	s_nop 0
	v_rcp_f32_e32 v159, v152
	v_rcp_f32_e32 v160, v153
	v_pk_add_f32 v[152:153], v[162:163], 1.0 op_sel_hi:[1,0]
	s_nop 0
	v_rcp_f32_e32 v161, v152
	v_rcp_f32_e32 v162, v153

; __device__ __forceinline__ u32x4 pack8(f32x4 v0, f32x4 v1) { u32x4 w; w.x = cvt_pk_bf16(v0[0], v0[1]); w.y = cvt_pk_bf16(v0[2], v0[3]); w.z = cvt_pk_bf16(v1[0], v1[1]); w.w = cvt_pk_bf16(v1[2], v1[3]); return w; }
; __device__ __forceinline__ f32x4 sigmoid4(f32x4 v) { const f32x2 a = sigmoid2((f32x2){v[0], v[1]}), b = sigmoid2((f32x2){v[2], v[3]}); return (f32x4){a.x, a.y, b.x, b.y}; }
; __device__ __forceinline__ f32x2 sigmoid2(f32x2 x) { const f32x2 t = x * (-LOG2E); f32x2 e; e.x = __builtin_amdgcn_exp2f(t.x); e.y = __builtin_amdgcn_exp2f(t.y);
;     const f32x2 d = e + 1.0f; f32x2 r; r.x = __builtin_amdgcn_rcpf(d.x); r.y = __builtin_amdgcn_rcpf(d.y); return r; }
;     __device__ __forceinline__ void operator()(const f32x4 (&acc)[2][2][4][2], const Unit& u, int ui, int wr, int wc, int fr, int fq) const {
;     ...
;             for (int m = 0; m < 4; ++m) { bf16_t* rowp = base + (size_t)(r0 + ai * 128 + m * 16) * ld + c0;
; #pragma unroll
;                 for (int bj = 0; bj < 2; ++bj) { f32x4 v0 = acc[ai][bj][m][0], v1 = acc[ai][bj][m][1];
;                     if (act == 2) { v0 = sigmoid4(v0); v1 = sigmoid4(v1); }
;                     *(u32x4*)(rowp + bj * 128) = pack8(v0, v1); } }
.Lp1a_2:
	s_and_b64 vcc, exec, s[6:7]
	s_cbranch_vccnz .Lp1f_3
	v_pk_mul_f32 v[156:157], v[108:109], s[60:61] op_sel_hi:[1,0]
	v_pk_mul_f32 v[158:159], v[110:111], s[60:61] op_sel_hi:[1,0]
	v_pk_mul_f32 v[160:161], v[96:97], s[60:61] op_sel_hi:[1,0]
	v_pk_mul_f32 v[162:163], v[98:99], s[60:61] op_sel_hi:[1,0]
	v_exp_f32_e32 v156, v156
	v_exp_f32_e32 v157, v157
	v_exp_f32_e32 v158, v158
	v_exp_f32_e32 v159, v159
	v_exp_f32_e32 v160, v160
	v_exp_f32_e32 v161, v161
	v_exp_f32_e32 v162, v162
	v_exp_f32_e32 v163, v163
	v_pk_add_f32 v[156:157], v[156:157], 1.0 op_sel_hi:[1,0]
	v_pk_add_f32 v[158:159], v[158:159], 1.0 op_sel_hi:[1,0]
	v_pk_add_f32 v[160:161], v[160:161], 1.0 op_sel_hi:[1,0]
	v_pk_add_f32 v[162:163], v[162:163], 1.0 op_sel_hi:[1,0]
	v_rcp_f32_e32 v155, v156
	v_rcp_f32_e32 v156, v157
	v_rcp_f32_e32 v157, v158
	v_rcp_f32_e32 v158, v159
	v_rcp_f32_e32 v159, v160
	v_rcp_f32_e32 v160, v161
	v_rcp_f32_e32 v161, v162
	v_rcp_f32_e32 v162, v163

; __device__ __forceinline__ u32x4 pack8(f32x4 v0, f32x4 v1) { u32x4 w; w.x = cvt_pk_bf16(v0[0], v0[1]); w.y = cvt_pk_bf16(v0[2], v0[3]); w.z = cvt_pk_bf16(v1[0], v1[1]); w.w = cvt_pk_bf16(v1[2], v1[3]); return w; }
; __device__ __forceinline__ f32x4 sigmoid4(f32x4 v) { const f32x2 a = sigmoid2((f32x2){v[0], v[1]}), b = sigmoid2((f32x2){v[2], v[3]}); return (f32x4){a.x, a.y, b.x, b.y}; }
; __device__ __forceinline__ f32x2 sigmoid2(f32x2 x) { const f32x2 t = x * (-LOG2E); f32x2 e; e.x = __builtin_amdgcn_exp2f(t.x); e.y = __builtin_amdgcn_exp2f(t.y);
;     const f32x2 d = e + 1.0f; f32x2 r; r.x = __builtin_amdgcn_rcpf(d.x); r.y = __builtin_amdgcn_rcpf(d.y); return r; }
;     __device__ __forceinline__ void operator()(const f32x4 (&acc)[2][2][4][2], const Unit& u, int ui, int wr, int wc, int fr, int fq) const {
;     ...
;             for (int m = 0; m < 4; ++m) { bf16_t* rowp = base + (size_t)(r0 + ai * 128 + m * 16) * ld + c0;
; #pragma unroll
;                 for (int bj = 0; bj < 2; ++bj) { f32x4 v0 = acc[ai][bj][m][0], v1 = acc[ai][bj][m][1];
;                     if (act == 2) { v0 = sigmoid4(v0); v1 = sigmoid4(v1); }
;                     *(u32x4*)(rowp + bj * 128) = pack8(v0, v1); } }
.Lp1a_3:
	s_and_b64 vcc, exec, s[6:7]
	s_cbranch_vccnz .Lp1f_4
	v_pk_mul_f32 v[152:153], v[88:89], s[60:61] op_sel_hi:[1,0]
	v_pk_mul_f32 v[156:157], v[90:91], s[60:61] op_sel_hi:[1,0]
	v_exp_f32_e32 v152, v152
	v_exp_f32_e32 v153, v153
	v_exp_f32_e32 v158, v156
	v_exp_f32_e32 v159, v157
	v_pk_mul_f32 v[160:161], v[86:87], s[60:61] op_sel_hi:[1,0]
	v_pk_add_f32 v[152:153], v[152:153], 1.0 op_sel_hi:[1,0]
	v_exp_f32_e32 v162, v160
	v_rcp_f32_e32 v155, v152
	v_rcp_f32_e32 v156, v153
	v_pk_add_f32 v[152:153], v[158:159], 1.0 op_sel_hi:[1,0]
	v_exp_f32_e32 v163, v161
	v_rcp_f32_e32 v157, v152
	v_rcp_f32_e32 v158, v153
	v_pk_mul_f32 v[152:153], v[84:85], s[60:61] op_sel_hi:[1,0]
	s_nop 0
	v_exp_f32_e32 v152, v152
	v_exp_f32_e32 v153, v153
	s_nop 0
	v_pk_add_f32 v[152:153], v[152:153], 1.0 op_sel_hi:[1,0]
	s_nop 0
	v_rcp_f32_e32 v159, v152
	v_rcp_f32_e32 v160, v153
	v_pk_add_f32 v[152:153], v[162:163], 1.0 op_sel_hi:[1,0]
	s_nop 0
	v_rcp_f32_e32 v161, v152
	v_rcp_f32_e32 v162, v153

; __device__ __forceinline__ u32x4 pack8(f32x4 v0, f32x4 v1) { u32x4 w; w.x = cvt_pk_bf16(v0[0], v0[1]); w.y = cvt_pk_bf16(v0[2], v0[3]); w.z = cvt_pk_bf16(v1[0], v1[1]); w.w = cvt_pk_bf16(v1[2], v1[3]); return w; }
; __device__ __forceinline__ f32x4 sigmoid4(f32x4 v) { const f32x2 a = sigmoid2((f32x2){v[0], v[1]}), b = sigmoid2((f32x2){v[2], v[3]}); return (f32x4){a.x, a.y, b.x, b.y}; }
; __device__ __forceinline__ f32x2 sigmoid2(f32x2 x) { const f32x2 t = x * (-LOG2E); f32x2 e; e.x = __builtin_amdgcn_exp2f(t.x); e.y = __builtin_amdgcn_exp2f(t.y);
;     const f32x2 d = e + 1.0f; f32x2 r; r.x = __builtin_amdgcn_rcpf(d.x); r.y = __builtin_amdgcn_rcpf(d.y); return r; }
;     __device__ __forceinline__ void operator()(const f32x4 (&acc)[2][2][4][2], const Unit& u, int ui, int wr, int wc, int fr, int fq) const {
;     ...
;             for (int m = 0; m < 4; ++m) { bf16_t* rowp = base + (size_t)(r0 + ai * 128 + m * 16) * ld + c0;
; #pragma unroll
;                 for (int bj = 0; bj < 2; ++bj) { f32x4 v0 = acc[ai][bj][m][0], v1 = acc[ai][bj][m][1];
;                     if (act == 2) { v0 = sigmoid4(v0); v1 = sigmoid4(v1); }
;                     *(u32x4*)(rowp + bj * 128) = pack8(v0, v1); } }
.Lp1a_4:
	s_and_b64 vcc, exec, s[6:7]
	s_cbranch_vccnz .Lp1f_5
	v_pk_mul_f32 v[156:157], v[92:93], s[60:61] op_sel_hi:[1,0]
	v_pk_mul_f32 v[158:159], v[94:95], s[60:61] op_sel_hi:[1,0]
	v_pk_mul_f32 v[160:161], v[80:81], s[60:61] op_sel_hi:[1,0]
	v_pk_mul_f32 v[162:163], v[82:83], s[60:61] op_sel_hi:[1,0]
	v_exp_f32_e32 v156, v156
	v_exp_f32_e32 v157, v157
	v_exp_f32_e32 v158, v158
	v_exp_f32_e32 v159, v159
	v_exp_f32_e32 v160, v160
	v_exp_f32_e32 v161, v161
	v_exp_f32_e32 v162, v162
	v_exp_f32_e32 v163, v163
	v_pk_add_f32 v[156:157], v[156:157], 1.0 op_sel_hi:[1,0]
	v_pk_add_f32 v[158:159], v[158:159], 1.0 op_sel_hi:[1,0]
	v_pk_add_f32 v[160:161], v[160:161], 1.0 op_sel_hi:[1,0]
	v_pk_add_f32 v[162:163], v[162:163], 1.0 op_sel_hi:[1,0]
	v_rcp_f32_e32 v155, v156
	v_rcp_f32_e32 v156, v157
	v_rcp_f32_e32 v157, v158
	v_rcp_f32_e32 v158, v159
	v_rcp_f32_e32 v159, v160
	v_rcp_f32_e32 v160, v161
	v_rcp_f32_e32 v161, v162
	v_rcp_f32_e32 v162, v163

; __device__ __forceinline__ u32x4 pack8(f32x4 v0, f32x4 v1) { u32x4 w; w.x = cvt_pk_bf16(v0[0], v0[1]); w.y = cvt_pk_bf16(v0[2], v0[3]); w.z = cvt_pk_bf16(v1[0], v1[1]); w.w = cvt_pk_bf16(v1[2], v1[3]); return w; }
; __device__ __forceinline__ f32x4 sigmoid4(f32x4 v) { const f32x2 a = sigmoid2((f32x2){v[0], v[1]}), b = sigmoid2((f32x2){v[2], v[3]}); return (f32x4){a.x, a.y, b.x, b.y}; }
; __device__ __forceinline__ f32x2 sigmoid2(f32x2 x) { const f32x2 t = x * (-LOG2E); f32x2 e; e.x = __builtin_amdgcn_exp2f(t.x); e.y = __builtin_amdgcn_exp2f(t.y);
;     const f32x2 d = e + 1.0f; f32x2 r; r.x = __builtin_amdgcn_rcpf(d.x); r.y = __builtin_amdgcn_rcpf(d.y); return r; }
;     __device__ __forceinline__ void operator()(const f32x4 (&acc)[2][2][4][2], const Unit& u, int ui, int wr, int wc, int fr, int fq) const {
;     ...
;             for (int m = 0; m < 4; ++m) { bf16_t* rowp = base + (size_t)(r0 + ai * 128 + m * 16) * ld + c0;
; #pragma unroll
;                 for (int bj = 0; bj < 2; ++bj) { f32x4 v0 = acc[ai][bj][m][0], v1 = acc[ai][bj][m][1];
;                     if (act == 2) { v0 = sigmoid4(v0); v1 = sigmoid4(v1); }
;                     *(u32x4*)(rowp + bj * 128) = pack8(v0, v1); } }
.Lp1a_5:
	s_and_b64 vcc, exec, s[6:7]
	s_cbranch_vccnz .Lp1f_6
	v_pk_mul_f32 v[152:153], v[72:73], s[60:61] op_sel_hi:[1,0]
	v_pk_mul_f32 v[156:157], v[74:75], s[60:61] op_sel_hi:[1,0]
	v_exp_f32_e32 v152, v152
	v_exp_f32_e32 v153, v153
	v_exp_f32_e32 v158, v156
	v_exp_f32_e32 v159, v157
	v_pk_mul_f32 v[160:161], v[70:71], s[60:61] op_sel_hi:[1,0]
	v_pk_add_f32 v[152:153], v[152:153], 1.0 op_sel_hi:[1,0]
	v_exp_f32_e32 v162, v160
	v_rcp_f32_e32 v155, v152
	v_rcp_f32_e32 v156, v153
	v_pk_add_f32 v[152:153], v[158:159], 1.0 op_sel_hi:[1,0]
	v_exp_f32_e32 v163, v161
	v_rcp_f32_e32 v157, v152
	v_rcp_f32_e32 v158, v153
	v_pk_mul_f32 v[152:153], v[68:69], s[60:61] op_sel_hi:[1,0]
	s_nop 0
	v_exp_f32_e32 v152, v152
	v_exp_f32_e32 v153, v153
	s_nop 0
	v_pk_add_f32 v[152:153], v[152:153], 1.0 op_sel_hi:[1,0]
	s_nop 0
	v_rcp_f32_e32 v159, v152
	v_rcp_f32_e32 v160, v153
	v_pk_add_f32 v[152:153], v[162:163], 1.0 op_sel_hi:[1,0]
	s_nop 0
	v_rcp_f32_e32 v161, v152
	v_rcp_f32_e32 v162, v153

; __device__ __forceinline__ u32x4 pack8(f32x4 v0, f32x4 v1) { u32x4 w; w.x = cvt_pk_bf16(v0[0], v0[1]); w.y = cvt_pk_bf16(v0[2], v0[3]); w.z = cvt_pk_bf16(v1[0], v1[1]); w.w = cvt_pk_bf16(v1[2], v1[3]); return w; }
; __device__ __forceinline__ f32x4 sigmoid4(f32x4 v) { const f32x2 a = sigmoid2((f32x2){v[0], v[1]}), b = sigmoid2((f32x2){v[2], v[3]}); return (f32x4){a.x, a.y, b.x, b.y}; }
; __device__ __forceinline__ f32x2 sigmoid2(f32x2 x) { const f32x2 t = x * (-LOG2E); f32x2 e; e.x = __builtin_amdgcn_exp2f(t.x); e.y = __builtin_amdgcn_exp2f(t.y);
;     const f32x2 d = e + 1.0f; f32x2 r; r.x = __builtin_amdgcn_rcpf(d.x); r.y = __builtin_amdgcn_rcpf(d.y); return r; }
;     __device__ __forceinline__ void operator()(const f32x4 (&acc)[2][2][4][2], const Unit& u, int ui, int wr, int wc, int fr, int fq) const {
;     ...
;             for (int m = 0; m < 4; ++m) { bf16_t* rowp = base + (size_t)(r0 + ai * 128 + m * 16) * ld + c0;
; #pragma unroll
;                 for (int bj = 0; bj < 2; ++bj) { f32x4 v0 = acc[ai][bj][m][0], v1 = acc[ai][bj][m][1];
;                     if (act == 2) { v0 = sigmoid4(v0); v1 = sigmoid4(v1); }
;                     *(u32x4*)(rowp + bj * 128) = pack8(v0, v1); } }
.Lp1a_6:
	s_and_b64 vcc, exec, s[6:7]
	s_cbranch_vccnz .Lp1f_7
	v_pk_mul_f32 v[154:155], v[76:77], s[60:61] op_sel_hi:[1,0]
	v_pk_mul_f32 v[156:157], v[78:79], s[60:61] op_sel_hi:[1,0]
	v_pk_mul_f32 v[158:159], v[64:65], s[60:61] op_sel_hi:[1,0]
	v_pk_mul_f32 v[160:161], v[66:67], s[60:61] op_sel_hi:[1,0]
	v_exp_f32_e32 v154, v154
	v_exp_f32_e32 v155, v155
	v_exp_f32_e32 v156, v156
	v_exp_f32_e32 v157, v157
	v_exp_f32_e32 v158, v158
	v_exp_f32_e32 v159, v159
	v_exp_f32_e32 v160, v160
	v_exp_f32_e32 v161, v161
	v_pk_add_f32 v[154:155], v[154:155], 1.0 op_sel_hi:[1,0]
	v_pk_add_f32 v[156:157], v[156:157], 1.0 op_sel_hi:[1,0]
	v_pk_add_f32 v[158:159], v[158:159], 1.0 op_sel_hi:[1,0]
	v_pk_add_f32 v[160:161], v[160:161], 1.0 op_sel_hi:[1,0]
	v_rcp_f32_e32 v154, v154
	v_rcp_f32_e32 v155, v155
	v_rcp_f32_e32 v156, v156
	v_rcp_f32_e32 v157, v157
	v_rcp_f32_e32 v158, v158
	v_rcp_f32_e32 v159, v159
	v_rcp_f32_e32 v160, v160
	v_rcp_f32_e32 v161, v161

; __device__ __forceinline__ u32x4 pack8(f32x4 v0, f32x4 v1) { u32x4 w; w.x = cvt_pk_bf16(v0[0], v0[1]); w.y = cvt_pk_bf16(v0[2], v0[3]); w.z = cvt_pk_bf16(v1[0], v1[1]); w.w = cvt_pk_bf16(v1[2], v1[3]); return w; }
; __device__ __forceinline__ f32x4 sigmoid4(f32x4 v) { const f32x2 a = sigmoid2((f32x2){v[0], v[1]}), b = sigmoid2((f32x2){v[2], v[3]}); return (f32x4){a.x, a.y, b.x, b.y}; }
; __device__ __forceinline__ f32x2 sigmoid2(f32x2 x) { const f32x2 t = x * (-LOG2E); f32x2 e; e.x = __builtin_amdgcn_exp2f(t.x); e.y = __builtin_amdgcn_exp2f(t.y);
;     const f32x2 d = e + 1.0f; f32x2 r; r.x = __builtin_amdgcn_rcpf(d.x); r.y = __builtin_amdgcn_rcpf(d.y); return r; }
;     __device__ __forceinline__ void operator()(const f32x4 (&acc)[2][2][4][2], const Unit& u, int ui, int wr, int wc, int fr, int fq) const {
;     ...
;             for (int m = 0; m < 4; ++m) { bf16_t* rowp = base + (size_t)(r0 + ai * 128 + m * 16) * ld + c0;
; #pragma unroll
;                 for (int bj = 0; bj < 2; ++bj) { f32x4 v0 = acc[ai][bj][m][0], v1 = acc[ai][bj][m][1];
;                     if (act == 2) { v0 = sigmoid4(v0); v1 = sigmoid4(v1); }
;                     *(u32x4*)(rowp + bj * 128) = pack8(v0, v1); } }
.Lp1a_7:
	s_and_b64 vcc, exec, s[6:7]
	s_cbranch_vccnz .Lp1f_8
	v_pk_mul_f32 v[152:153], v[56:57], s[60:61] op_sel_hi:[1,0]
	v_pk_mul_f32 v[154:155], v[58:59], s[60:61] op_sel_hi:[1,0]
	v_exp_f32_e32 v152, v152
	v_exp_f32_e32 v153, v153
	v_exp_f32_e32 v156, v154
	v_exp_f32_e32 v157, v155
	v_pk_mul_f32 v[158:159], v[54:55], s[60:61] op_sel_hi:[1,0]
	v_pk_add_f32 v[152:153], v[152:153], 1.0 op_sel_hi:[1,0]
	v_exp_f32_e32 v160, v158
	v_rcp_f32_e32 v154, v152
	v_rcp_f32_e32 v155, v153
	v_pk_add_f32 v[152:153], v[156:157], 1.0 op_sel_hi:[1,0]
	v_exp_f32_e32 v161, v159
	v_rcp_f32_e32 v156, v152
	v_rcp_f32_e32 v157, v153
	v_pk_mul_f32 v[152:153], v[52:53], s[60:61] op_sel_hi:[1,0]
	s_nop 0
	v_exp_f32_e32 v152, v152
	v_exp_f32_e32 v153, v153
	s_nop 0
	v_pk_add_f32 v[152:153], v[152:153], 1.0 op_sel_hi:[1,0]
	s_nop 0
	v_rcp_f32_e32 v158, v152
	v_rcp_f32_e32 v159, v153
	v_pk_add_f32 v[152:153], v[160:161], 1.0 op_sel_hi:[1,0]
	s_nop 0
	v_rcp_f32_e32 v160, v152
	v_rcp_f32_e32 v161, v153

; __device__ __forceinline__ u32x4 pack8(f32x4 v0, f32x4 v1) { u32x4 w; w.x = cvt_pk_bf16(v0[0], v0[1]); w.y = cvt_pk_bf16(v0[2], v0[3]); w.z = cvt_pk_bf16(v1[0], v1[1]); w.w = cvt_pk_bf16(v1[2], v1[3]); return w; }
; __device__ __forceinline__ f32x4 sigmoid4(f32x4 v) { const f32x2 a = sigmoid2((f32x2){v[0], v[1]}), b = sigmoid2((f32x2){v[2], v[3]}); return (f32x4){a.x, a.y, b.x, b.y}; }
; __device__ __forceinline__ f32x2 sigmoid2(f32x2 x) { const f32x2 t = x * (-LOG2E); f32x2 e; e.x = __builtin_amdgcn_exp2f(t.x); e.y = __builtin_amdgcn_exp2f(t.y);
;     const f32x2 d = e + 1.0f; f32x2 r; r.x = __builtin_amdgcn_rcpf(d.x); r.y = __builtin_amdgcn_rcpf(d.y); return r; }
;     __device__ __forceinline__ void operator()(const f32x4 (&acc)[2][2][4][2], const Unit& u, int ui, int wr, int wc, int fr, int fq) const {
;     ...
;             for (int m = 0; m < 4; ++m) { bf16_t* rowp = base + (size_t)(r0 + ai * 128 + m * 16) * ld + c0;
; #pragma unroll
;                 for (int bj = 0; bj < 2; ++bj) { f32x4 v0 = acc[ai][bj][m][0], v1 = acc[ai][bj][m][1];
;                     if (act == 2) { v0 = sigmoid4(v0); v1 = sigmoid4(v1); }
;                     *(u32x4*)(rowp + bj * 128) = pack8(v0, v1); } }
.Lp1a_8:
	s_and_b64 vcc, exec, s[6:7]
	s_cbranch_vccnz .Lp1f_9
	v_pk_mul_f32 v[154:155], v[60:61], s[60:61] op_sel_hi:[1,0]
	v_pk_mul_f32 v[156:157], v[62:63], s[60:61] op_sel_hi:[1,0]
	v_pk_mul_f32 v[158:159], v[48:49], s[60:61] op_sel_hi:[1,0]
	v_pk_mul_f32 v[160:161], v[50:51], s[60:61] op_sel_hi:[1,0]
	v_exp_f32_e32 v154, v154
	v_exp_f32_e32 v155, v155
	v_exp_f32_e32 v156, v156
	v_exp_f32_e32 v157, v157
	v_exp_f32_e32 v158, v158
	v_exp_f32_e32 v159, v159
	v_exp_f32_e32 v160, v160
	v_exp_f32_e32 v161, v161
	v_pk_add_f32 v[154:155], v[154:155], 1.0 op_sel_hi:[1,0]
	v_pk_add_f32 v[156:157], v[156:157], 1.0 op_sel_hi:[1,0]
	v_pk_add_f32 v[158:159], v[158:159], 1.0 op_sel_hi:[1,0]
	v_pk_add_f32 v[160:161], v[160:161], 1.0 op_sel_hi:[1,0]
	v_rcp_f32_e32 v154, v154
	v_rcp_f32_e32 v155, v155
	v_rcp_f32_e32 v156, v156
	v_rcp_f32_e32 v157, v157
	v_rcp_f32_e32 v158, v158
	v_rcp_f32_e32 v159, v159
	v_rcp_f32_e32 v160, v160
	v_rcp_f32_e32 v161, v161

; __device__ __forceinline__ u32x4 pack8(f32x4 v0, f32x4 v1) { u32x4 w; w.x = cvt_pk_bf16(v0[0], v0[1]); w.y = cvt_pk_bf16(v0[2], v0[3]); w.z = cvt_pk_bf16(v1[0], v1[1]); w.w = cvt_pk_bf16(v1[2], v1[3]); return w; }
; __device__ __forceinline__ f32x4 sigmoid4(f32x4 v) { const f32x2 a = sigmoid2((f32x2){v[0], v[1]}), b = sigmoid2((f32x2){v[2], v[3]}); return (f32x4){a.x, a.y, b.x, b.y}; }
; __device__ __forceinline__ f32x2 sigmoid2(f32x2 x) { const f32x2 t = x * (-LOG2E); f32x2 e; e.x = __builtin_amdgcn_exp2f(t.x); e.y = __builtin_amdgcn_exp2f(t.y);
;     const f32x2 d = e + 1.0f; f32x2 r; r.x = __builtin_amdgcn_rcpf(d.x); r.y = __builtin_amdgcn_rcpf(d.y); return r; }
;     __device__ __forceinline__ void operator()(const f32x4 (&acc)[2][2][4][2], const Unit& u, int ui, int wr, int wc, int fr, int fq) const {
;     ...
;             for (int m = 0; m < 4; ++m) { bf16_t* rowp = base + (size_t)(r0 + ai * 128 + m * 16) * ld + c0;
; #pragma unroll
;                 for (int bj = 0; bj < 2; ++bj) { f32x4 v0 = acc[ai][bj][m][0], v1 = acc[ai][bj][m][1];
;                     if (act == 2) { v0 = sigmoid4(v0); v1 = sigmoid4(v1); }
;                     *(u32x4*)(rowp + bj * 128) = pack8(v0, v1); } }
.Lp1a_9:
	s_and_b64 vcc, exec, s[6:7]
	s_cbranch_vccnz .Lp1f_10
	v_pk_mul_f32 v[152:153], v[40:41], s[60:61] op_sel_hi:[1,0]
	v_pk_mul_f32 v[154:155], v[42:43], s[60:61] op_sel_hi:[1,0]
	v_exp_f32_e32 v152, v152
	v_exp_f32_e32 v153, v153
	v_exp_f32_e32 v156, v154
	v_exp_f32_e32 v157, v155
	v_pk_mul_f32 v[158:159], v[38:39], s[60:61] op_sel_hi:[1,0]
	v_pk_add_f32 v[152:153], v[152:153], 1.0 op_sel_hi:[1,0]
	v_exp_f32_e32 v160, v158
	v_rcp_f32_e32 v154, v152
	v_rcp_f32_e32 v155, v153
	v_pk_add_f32 v[152:153], v[156:157], 1.0 op_sel_hi:[1,0]
	v_exp_f32_e32 v161, v159
	v_rcp_f32_e32 v156, v152
	v_rcp_f32_e32 v157, v153
	v_pk_mul_f32 v[152:153], v[36:37], s[60:61] op_sel_hi:[1,0]
	s_nop 0
	v_exp_f32_e32 v152, v152
	v_exp_f32_e32 v153, v153
	s_nop 0
	v_pk_add_f32 v[152:153], v[152:153], 1.0 op_sel_hi:[1,0]
	s_nop 0
	v_rcp_f32_e32 v158, v152
	v_rcp_f32_e32 v159, v153
	v_pk_add_f32 v[152:153], v[160:161], 1.0 op_sel_hi:[1,0]
	s_nop 0
	v_rcp_f32_e32 v160, v152
	v_rcp_f32_e32 v161, v153

; __device__ __forceinline__ u32x4 pack8(f32x4 v0, f32x4 v1) { u32x4 w; w.x = cvt_pk_bf16(v0[0], v0[1]); w.y = cvt_pk_bf16(v0[2], v0[3]); w.z = cvt_pk_bf16(v1[0], v1[1]); w.w = cvt_pk_bf16(v1[2], v1[3]); return w; }
; __device__ __forceinline__ f32x4 sigmoid4(f32x4 v) { const f32x2 a = sigmoid2((f32x2){v[0], v[1]}), b = sigmoid2((f32x2){v[2], v[3]}); return (f32x4){a.x, a.y, b.x, b.y}; }
; __device__ __forceinline__ f32x2 sigmoid2(f32x2 x) { const f32x2 t = x * (-LOG2E); f32x2 e; e.x = __builtin_amdgcn_exp2f(t.x); e.y = __builtin_amdgcn_exp2f(t.y);
;     const f32x2 d = e + 1.0f; f32x2 r; r.x = __builtin_amdgcn_rcpf(d.x); r.y = __builtin_amdgcn_rcpf(d.y); return r; }
;     __device__ __forceinline__ void operator()(const f32x4 (&acc)[2][2][4][2], const Unit& u, int ui, int wr, int wc, int fr, int fq) const {
;     ...
;             for (int m = 0; m < 4; ++m) { bf16_t* rowp = base + (size_t)(r0 + ai * 128 + m * 16) * ld + c0;
; #pragma unroll
;                 for (int bj = 0; bj < 2; ++bj) { f32x4 v0 = acc[ai][bj][m][0], v1 = acc[ai][bj][m][1];
;                     if (act == 2) { v0 = sigmoid4(v0); v1 = sigmoid4(v1); }
;                     *(u32x4*)(rowp + bj * 128) = pack8(v0, v1); } }
.Lp1a_10:
	s_and_b64 vcc, exec, s[6:7]
	s_cbranch_vccnz .Lp1f_11
	v_pk_mul_f32 v[154:155], v[44:45], s[60:61] op_sel_hi:[1,0]
	v_pk_mul_f32 v[156:157], v[46:47], s[60:61] op_sel_hi:[1,0]
	v_pk_mul_f32 v[158:159], v[32:33], s[60:61] op_sel_hi:[1,0]
	v_pk_mul_f32 v[160:161], v[34:35], s[60:61] op_sel_hi:[1,0]
	v_exp_f32_e32 v154, v154
	v_exp_f32_e32 v155, v155
	v_exp_f32_e32 v156, v156
	v_exp_f32_e32 v157, v157
	v_exp_f32_e32 v158, v158
	v_exp_f32_e32 v159, v159
	v_exp_f32_e32 v160, v160
	v_exp_f32_e32 v161, v161
	v_pk_add_f32 v[154:155], v[154:155], 1.0 op_sel_hi:[1,0]
	v_pk_add_f32 v[156:157], v[156:157], 1.0 op_sel_hi:[1,0]
	v_pk_add_f32 v[158:159], v[158:159], 1.0 op_sel_hi:[1,0]
	v_pk_add_f32 v[160:161], v[160:161], 1.0 op_sel_hi:[1,0]
	v_rcp_f32_e32 v154, v154
	v_rcp_f32_e32 v155, v155
	v_rcp_f32_e32 v156, v156
	v_rcp_f32_e32 v157, v157
	v_rcp_f32_e32 v158, v158
	v_rcp_f32_e32 v159, v159
	v_rcp_f32_e32 v160, v160
	v_rcp_f32_e32 v161, v161

; __device__ __forceinline__ u32x4 pack8(f32x4 v0, f32x4 v1) { u32x4 w; w.x = cvt_pk_bf16(v0[0], v0[1]); w.y = cvt_pk_bf16(v0[2], v0[3]); w.z = cvt_pk_bf16(v1[0], v1[1]); w.w = cvt_pk_bf16(v1[2], v1[3]); return w; }
; __device__ __forceinline__ f32x4 sigmoid4(f32x4 v) { const f32x2 a = sigmoid2((f32x2){v[0], v[1]}), b = sigmoid2((f32x2){v[2], v[3]}); return (f32x4){a.x, a.y, b.x, b.y}; }
; __device__ __forceinline__ f32x2 sigmoid2(f32x2 x) { const f32x2 t = x * (-LOG2E); f32x2 e; e.x = __builtin_amdgcn_exp2f(t.x); e.y = __builtin_amdgcn_exp2f(t.y);
;     const f32x2 d = e + 1.0f; f32x2 r; r.x = __builtin_amdgcn_rcpf(d.x); r.y = __builtin_amdgcn_rcpf(d.y); return r; }
;     __device__ __forceinline__ void operator()(const f32x4 (&acc)[2][2][4][2], const Unit& u, int ui, int wr, int wc, int fr, int fq) const {
;     ...
;             for (int m = 0; m < 4; ++m) { bf16_t* rowp = base + (size_t)(r0 + ai * 128 + m * 16) * ld + c0;
; #pragma unroll
;                 for (int bj = 0; bj < 2; ++bj) { f32x4 v0 = acc[ai][bj][m][0], v1 = acc[ai][bj][m][1];
;                     if (act == 2) { v0 = sigmoid4(v0); v1 = sigmoid4(v1); }
;                     *(u32x4*)(rowp + bj * 128) = pack8(v0, v1); } }
.Lp1a_11:
	s_and_b64 vcc, exec, s[6:7]
	s_cbranch_vccnz .Lp1f_12
	v_pk_mul_f32 v[152:153], v[24:25], s[60:61] op_sel_hi:[1,0]
	v_pk_mul_f32 v[154:155], v[26:27], s[60:61] op_sel_hi:[1,0]
	v_exp_f32_e32 v152, v152
	v_exp_f32_e32 v153, v153
	v_exp_f32_e32 v156, v154
	v_exp_f32_e32 v157, v155
	v_pk_mul_f32 v[158:159], v[22:23], s[60:61] op_sel_hi:[1,0]
	v_pk_add_f32 v[152:153], v[152:153], 1.0 op_sel_hi:[1,0]
	v_exp_f32_e32 v160, v158
	v_rcp_f32_e32 v154, v152
	v_rcp_f32_e32 v155, v153
	v_pk_add_f32 v[152:153], v[156:157], 1.0 op_sel_hi:[1,0]
	v_exp_f32_e32 v161, v159
	v_rcp_f32_e32 v156, v152
	v_rcp_f32_e32 v157, v153
	v_pk_mul_f32 v[152:153], v[20:21], s[60:61] op_sel_hi:[1,0]
	s_nop 0
	v_exp_f32_e32 v152, v152
	v_exp_f32_e32 v153, v153
	s_nop 0
	v_pk_add_f32 v[152:153], v[152:153], 1.0 op_sel_hi:[1,0]
	s_nop 0
	v_rcp_f32_e32 v158, v152
	v_rcp_f32_e32 v159, v153
	v_pk_add_f32 v[152:153], v[160:161], 1.0 op_sel_hi:[1,0]
	s_nop 0
	v_rcp_f32_e32 v160, v152
	v_rcp_f32_e32 v161, v153

; __device__ __forceinline__ u32x4 pack8(f32x4 v0, f32x4 v1) { u32x4 w; w.x = cvt_pk_bf16(v0[0], v0[1]); w.y = cvt_pk_bf16(v0[2], v0[3]); w.z = cvt_pk_bf16(v1[0], v1[1]); w.w = cvt_pk_bf16(v1[2], v1[3]); return w; }
; __device__ __forceinline__ f32x4 sigmoid4(f32x4 v) { const f32x2 a = sigmoid2((f32x2){v[0], v[1]}), b = sigmoid2((f32x2){v[2], v[3]}); return (f32x4){a.x, a.y, b.x, b.y}; }
; __device__ __forceinline__ f32x2 sigmoid2(f32x2 x) { const f32x2 t = x * (-LOG2E); f32x2 e; e.x = __builtin_amdgcn_exp2f(t.x); e.y = __builtin_amdgcn_exp2f(t.y);
;     const f32x2 d = e + 1.0f; f32x2 r; r.x = __builtin_amdgcn_rcpf(d.x); r.y = __builtin_amdgcn_rcpf(d.y); return r; }
;     __device__ __forceinline__ void operator()(const f32x4 (&acc)[2][2][4][2], const Unit& u, int ui, int wr, int wc, int fr, int fq) const {
;     ...
;             for (int m = 0; m < 4; ++m) { bf16_t* rowp = base + (size_t)(r0 + ai * 128 + m * 16) * ld + c0;
; #pragma unroll
;                 for (int bj = 0; bj < 2; ++bj) { f32x4 v0 = acc[ai][bj][m][0], v1 = acc[ai][bj][m][1];
;                     if (act == 2) { v0 = sigmoid4(v0); v1 = sigmoid4(v1); }
;                     *(u32x4*)(rowp + bj * 128) = pack8(v0, v1); } }
.Lp1a_12:
	s_and_b64 vcc, exec, s[6:7]
	s_cbranch_vccnz .Lp1f_13
	v_pk_mul_f32 v[154:155], v[28:29], s[60:61] op_sel_hi:[1,0]
	v_pk_mul_f32 v[156:157], v[30:31], s[60:61] op_sel_hi:[1,0]
	v_pk_mul_f32 v[158:159], v[16:17], s[60:61] op_sel_hi:[1,0]
	v_pk_mul_f32 v[160:161], v[18:19], s[60:61] op_sel_hi:[1,0]
	v_exp_f32_e32 v154, v154
	v_exp_f32_e32 v155, v155
	v_exp_f32_e32 v156, v156
	v_exp_f32_e32 v157, v157
	v_exp_f32_e32 v158, v158
	v_exp_f32_e32 v159, v159
	v_exp_f32_e32 v160, v160
	v_exp_f32_e32 v161, v161
	v_pk_add_f32 v[154:155], v[154:155], 1.0 op_sel_hi:[1,0]
	v_pk_add_f32 v[156:157], v[156:157], 1.0 op_sel_hi:[1,0]
	v_pk_add_f32 v[158:159], v[158:159], 1.0 op_sel_hi:[1,0]
	v_pk_add_f32 v[160:161], v[160:161], 1.0 op_sel_hi:[1,0]
	v_rcp_f32_e32 v154, v154
	v_rcp_f32_e32 v155, v155
	v_rcp_f32_e32 v156, v156
	v_rcp_f32_e32 v157, v157
	v_rcp_f32_e32 v158, v158
	v_rcp_f32_e32 v159, v159
	v_rcp_f32_e32 v160, v160
	v_rcp_f32_e32 v161, v161

; __device__ __forceinline__ u32x4 pack8(f32x4 v0, f32x4 v1) { u32x4 w; w.x = cvt_pk_bf16(v0[0], v0[1]); w.y = cvt_pk_bf16(v0[2], v0[3]); w.z = cvt_pk_bf16(v1[0], v1[1]); w.w = cvt_pk_bf16(v1[2], v1[3]); return w; }
; __device__ __forceinline__ f32x4 sigmoid4(f32x4 v) { const f32x2 a = sigmoid2((f32x2){v[0], v[1]}), b = sigmoid2((f32x2){v[2], v[3]}); return (f32x4){a.x, a.y, b.x, b.y}; }
; __device__ __forceinline__ f32x2 sigmoid2(f32x2 x) { const f32x2 t = x * (-LOG2E); f32x2 e; e.x = __builtin_amdgcn_exp2f(t.x); e.y = __builtin_amdgcn_exp2f(t.y);
;     const f32x2 d = e + 1.0f; f32x2 r; r.x = __builtin_amdgcn_rcpf(d.x); r.y = __builtin_amdgcn_rcpf(d.y); return r; }
;     __device__ __forceinline__ void operator()(const f32x4 (&acc)[2][2][4][2], const Unit& u, int ui, int wr, int wc, int fr, int fq) const {
;     ...
;             for (int m = 0; m < 4; ++m) { bf16_t* rowp = base + (size_t)(r0 + ai * 128 + m * 16) * ld + c0;
; #pragma unroll
;                 for (int bj = 0; bj < 2; ++bj) { f32x4 v0 = acc[ai][bj][m][0], v1 = acc[ai][bj][m][1];
;                     if (act == 2) { v0 = sigmoid4(v0); v1 = sigmoid4(v1); }
;                     *(u32x4*)(rowp + bj * 128) = pack8(v0, v1); } }
.Lp1a_13:
	s_and_b64 vcc, exec, s[6:7]
	s_cbranch_vccnz .Lp1f_14
	v_pk_mul_f32 v[152:153], v[8:9], s[60:61] op_sel_hi:[1,0]
	v_pk_mul_f32 v[154:155], v[10:11], s[60:61] op_sel_hi:[1,0]
	v_pk_mul_f32 v[156:157], v[4:5], s[60:61] op_sel_hi:[1,0]
	v_pk_mul_f32 v[158:159], v[6:7], s[60:61] op_sel_hi:[1,0]
	v_exp_f32_e32 v152, v152
	v_exp_f32_e32 v153, v153
	v_exp_f32_e32 v154, v154
	v_exp_f32_e32 v155, v155
	v_exp_f32_e32 v156, v156
	v_exp_f32_e32 v157, v157
	v_exp_f32_e32 v158, v158
	v_exp_f32_e32 v159, v159
	v_pk_add_f32 v[152:153], v[152:153], 1.0 op_sel_hi:[1,0]
	v_pk_add_f32 v[154:155], v[154:155], 1.0 op_sel_hi:[1,0]
	v_pk_add_f32 v[156:157], v[156:157], 1.0 op_sel_hi:[1,0]
	v_pk_add_f32 v[158:159], v[158:159], 1.0 op_sel_hi:[1,0]
	v_rcp_f32_e32 v152, v152
	v_rcp_f32_e32 v153, v153
	v_rcp_f32_e32 v154, v154
	v_rcp_f32_e32 v155, v155
	v_rcp_f32_e32 v156, v156
	v_rcp_f32_e32 v157, v157
	v_rcp_f32_e32 v158, v158
	v_rcp_f32_e32 v159, v159

; __device__ __forceinline__ u32x4 pack8(f32x4 v0, f32x4 v1) { u32x4 w; w.x = cvt_pk_bf16(v0[0], v0[1]); w.y = cvt_pk_bf16(v0[2], v0[3]); w.z = cvt_pk_bf16(v1[0], v1[1]); w.w = cvt_pk_bf16(v1[2], v1[3]); return w; }
; __device__ __forceinline__ f32x4 sigmoid4(f32x4 v) { const f32x2 a = sigmoid2((f32x2){v[0], v[1]}), b = sigmoid2((f32x2){v[2], v[3]}); return (f32x4){a.x, a.y, b.x, b.y}; }
; __device__ __forceinline__ f32x2 sigmoid2(f32x2 x) { const f32x2 t = x * (-LOG2E); f32x2 e; e.x = __builtin_amdgcn_exp2f(t.x); e.y = __builtin_amdgcn_exp2f(t.y);
;     const f32x2 d = e + 1.0f; f32x2 r; r.x = __builtin_amdgcn_rcpf(d.x); r.y = __builtin_amdgcn_rcpf(d.y); return r; }
;     __device__ __forceinline__ void operator()(const f32x4 (&acc)[2][2][4][2], const Unit& u, int ui, int wr, int wc, int fr, int fq) const {
;     ...
;             for (int m = 0; m < 4; ++m) { bf16_t* rowp = base + (size_t)(r0 + ai * 128 + m * 16) * ld + c0;
; #pragma unroll
;                 for (int bj = 0; bj < 2; ++bj) { f32x4 v0 = acc[ai][bj][m][0], v1 = acc[ai][bj][m][1];
;                     if (act == 2) { v0 = sigmoid4(v0); v1 = sigmoid4(v1); }
;                     *(u32x4*)(rowp + bj * 128) = pack8(v0, v1); } }
.Lp1a_14:
	s_and_b64 vcc, exec, s[6:7]
	s_cbranch_vccnz .Lp1f_15
	v_pk_mul_f32 v[152:153], v[12:13], s[60:61] op_sel_hi:[1,0]
	v_pk_mul_f32 v[154:155], v[14:15], s[60:61] op_sel_hi:[1,0]
	v_pk_mul_f32 v[156:157], v[0:1], s[60:61] op_sel_hi:[1,0]
	v_pk_mul_f32 v[158:159], v[2:3], s[60:61] op_sel_hi:[1,0]
	v_exp_f32_e32 v152, v152
	v_exp_f32_e32 v153, v153
	v_exp_f32_e32 v154, v154
	v_exp_f32_e32 v155, v155
	v_exp_f32_e32 v156, v156
	v_exp_f32_e32 v157, v157
	v_exp_f32_e32 v158, v158
	v_exp_f32_e32 v159, v159
	v_pk_add_f32 v[152:153], v[152:153], 1.0 op_sel_hi:[1,0]
	v_pk_add_f32 v[154:155], v[154:155], 1.0 op_sel_hi:[1,0]
	v_pk_add_f32 v[156:157], v[156:157], 1.0 op_sel_hi:[1,0]
	v_pk_add_f32 v[158:159], v[158:159], 1.0 op_sel_hi:[1,0]
	v_rcp_f32_e32 v140, v152
	v_rcp_f32_e32 v152, v153
	v_rcp_f32_e32 v153, v154
	v_rcp_f32_e32 v154, v155
	v_rcp_f32_e32 v155, v156
	v_rcp_f32_e32 v156, v157
	v_rcp_f32_e32 v157, v158
	v_rcp_f32_e32 v158, v159

; __device__ __forceinline__ u32x4 pack8(f32x4 v0, f32x4 v1) { u32x4 w; w.x = cvt_pk_bf16(v0[0], v0[1]); w.y = cvt_pk_bf16(v0[2], v0[3]); w.z = cvt_pk_bf16(v1[0], v1[1]); w.w = cvt_pk_bf16(v1[2], v1[3]); return w; }
; __device__ __forceinline__ f32x4 sigmoid4(f32x4 v) { const f32x2 a = sigmoid2((f32x2){v[0], v[1]}), b = sigmoid2((f32x2){v[2], v[3]}); return (f32x4){a.x, a.y, b.x, b.y}; }
;     __device__ __forceinline__ void operator()(const f32x4 (&acc)[2][2][4][2], const Unit& u, int ui, int wr, int wc, int fr, int fq) const {
;     ...
;         for (int ai = 0; ai < 2; ++ai)
; #pragma unroll
;             for (int m = 0; m < 4; ++m) { bf16_t* rowp = base + (size_t)(r0 + ai * 128 + m * 16) * ld + c0;
; #pragma unroll
;                 for (int bj = 0; bj < 2; ++bj) { f32x4 v0 = acc[ai][bj][m][0], v1 = acc[ai][bj][m][1];
;                     if (act == 2) { v0 = sigmoid4(v0); v1 = sigmoid4(v1); }
;                     *(u32x4*)(rowp + bj * 128) = pack8(v0, v1); } }
.Lp1a_15:
	s_mov_b64 s[6:7], 0

; __device__ __forceinline__ unsigned cvt_pk_bf16(float lo, float hi) { unsigned r; asm volatile("v_cvt_pk_bf16_f32 %0, %1, %2" : "=v"(r) : "v"(lo), "v"(hi)); return r; }
; __device__ __forceinline__ f32x4 sigmoid4(f32x4 v) { const f32x2 a = sigmoid2((f32x2){v[0], v[1]}), b = sigmoid2((f32x2){v[2], v[3]}); return (f32x4){a.x, a.y, b.x, b.y}; }
; __device__ __forceinline__ u32x4 pack8(f32x4 v0, f32x4 v1) { u32x4 w; w.x = cvt_pk_bf16(v0[0], v0[1]); w.y = cvt_pk_bf16(v0[2], v0[3]); w.z = cvt_pk_bf16(v1[0], v1[1]); w.w = cvt_pk_bf16(v1[2], v1[3]); return w; }
;     __device__ __forceinline__ void operator()(const f32x4 (&acc)[2][2][4][2], const Unit& u, int ui, int wr, int wc, int fr, int fq) const {
;     ...
;         const int r0 = row0 + wr * 64 + fr, c0 = col0 + wc * 32 + 8 * fq;
; #pragma unroll
;         for (int ai = 0; ai < 2; ++ai)
; #pragma unroll
;             for (int m = 0; m < 4; ++m) { bf16_t* rowp = base + (size_t)(r0 + ai * 128 + m * 16) * ld + c0;
; #pragma unroll
;                 for (int bj = 0; bj < 2; ++bj) { f32x4 v0 = acc[ai][bj][m][0], v1 = acc[ai][bj][m][1];
;                     if (act == 2) { v0 = sigmoid4(v0); v1 = sigmoid4(v1); }
;                     *(u32x4*)(rowp + bj * 128) = pack8(v0, v1); } }
.Lp1f_0:
	v_add_u32_e32 v150, s20, v204
	v_add_u32_e32 v140, s63, v129
	v_ashrrev_i32_e32 v151, 31, v150
	v_ashrrev_i32_e32 v152, 31, v140
	v_lshl_add_u64 v[150:151], v[150:151], 1, s[80:81]
	v_mul_lo_u32 v154, s78, v152
	v_mul_lo_u32 v163, s79, v140
	v_mad_u64_u32 v[152:153], s[80:81], s78, v140, 0
	v_add3_u32 v153, v153, v154, v163
	v_lshl_add_u64 v[152:153], v[152:153], 1, v[150:151]
	v_cvt_pk_bf16_f32 v156, v120, v121
	v_cvt_pk_bf16_f32 v157, v122, v123
	v_cvt_pk_bf16_f32 v158, v116, v117
	v_cvt_pk_bf16_f32 v159, v118, v119
	global_store_dwordx4 v[152:153], v[156:159], off
	s_branch .Lp1a_0
.Lp1f_1:
	v_cvt_pk_bf16_f32 v156, v124, v125
	v_cvt_pk_bf16_f32 v157, v126, v127
	v_cvt_pk_bf16_f32 v158, v112, v113
	v_cvt_pk_bf16_f32 v159, v114, v115
	global_store_dwordx4 v[152:153], v[156:159], off offset:256
	s_branch .Lp1a_1
.Lp1f_2:
	v_or_b32_e32 v152, 16, v140
	v_mul_lo_u32 v163, s79, v152
	v_mad_u64_u32 v[152:153], s[80:81], s78, v152, 0
	v_add3_u32 v153, v153, v154, v163
	v_lshl_add_u64 v[152:153], v[152:153], 1, v[150:151]
	v_cvt_pk_bf16_f32 v156, v104, v105
	v_cvt_pk_bf16_f32 v157, v106, v107
	v_cvt_pk_bf16_f32 v158, v100, v101
	v_cvt_pk_bf16_f32 v159, v102, v103
	global_store_dwordx4 v[152:153], v[156:159], off
	s_branch .Lp1a_2
.Lp1f_3:
	v_cvt_pk_bf16_f32 v156, v108, v109
	v_cvt_pk_bf16_f32 v157, v110, v111
	v_cvt_pk_bf16_f32 v158, v96, v97
	v_cvt_pk_bf16_f32 v159, v98, v99
	global_store_dwordx4 v[152:153], v[156:159], off offset:256
	s_branch .Lp1a_3
.Lp1f_4:
	v_or_b32_e32 v152, 32, v140
	v_mul_lo_u32 v163, s79, v152
	v_mad_u64_u32 v[152:153], s[80:81], s78, v152, 0
	v_add3_u32 v153, v153, v154, v163
	v_lshl_add_u64 v[152:153], v[152:153], 1, v[150:151]
	v_cvt_pk_bf16_f32 v156, v88, v89
	v_cvt_pk_bf16_f32 v157, v90, v91
	v_cvt_pk_bf16_f32 v158, v84, v85
	v_cvt_pk_bf16_f32 v159, v86, v87
	global_store_dwordx4 v[152:153], v[156:159], off
	s_branch .Lp1a_4
.Lp1f_5:
	v_cvt_pk_bf16_f32 v156, v92, v93
	v_cvt_pk_bf16_f32 v157, v94, v95
	v_cvt_pk_bf16_f32 v158, v80, v81
	v_cvt_pk_bf16_f32 v159, v82, v83
	global_store_dwordx4 v[152:153], v[156:159], off offset:256
	s_branch .Lp1a_5
.Lp1f_6:
	v_or_b32_e32 v152, 48, v140
	v_mul_lo_u32 v163, s79, v152
	v_mad_u64_u32 v[152:153], s[80:81], s78, v152, 0
	v_add3_u32 v153, v153, v154, v163
	v_lshl_add_u64 v[152:153], v[152:153], 1, v[150:151]
	v_cvt_pk_bf16_f32 v154, v72, v73
	v_cvt_pk_bf16_f32 v155, v74, v75
	v_cvt_pk_bf16_f32 v156, v68, v69
	v_cvt_pk_bf16_f32 v157, v70, v71
	global_store_dwordx4 v[152:153], v[154:157], off
	s_branch .Lp1a_6
.Lp1f_7:
	v_cvt_pk_bf16_f32 v154, v76, v77
	v_cvt_pk_bf16_f32 v155, v78, v79
	v_cvt_pk_bf16_f32 v156, v64, v65
	v_cvt_pk_bf16_f32 v157, v66, v67
	global_store_dwordx4 v[152:153], v[154:157], off offset:256
	s_branch .Lp1a_7
.Lp1f_8:
	v_add_u32_e32 v152, 0x80, v140
	v_ashrrev_i32_e32 v153, 31, v152
	v_mul_lo_u32 v162, s78, v153
	v_mul_lo_u32 v163, s79, v152
	v_mad_u64_u32 v[152:153], s[80:81], s78, v152, 0
	v_add3_u32 v153, v153, v162, v163
	v_lshl_add_u64 v[152:153], v[152:153], 1, v[150:151]
	v_cvt_pk_bf16_f32 v154, v56, v57
	v_cvt_pk_bf16_f32 v155, v58, v59
	v_cvt_pk_bf16_f32 v156, v52, v53
	v_cvt_pk_bf16_f32 v157, v54, v55
	global_store_dwordx4 v[152:153], v[154:157], off
	s_branch .Lp1a_8
.Lp1f_9:
	v_cvt_pk_bf16_f32 v154, v60, v61
	v_cvt_pk_bf16_f32 v155, v62, v63
	v_cvt_pk_bf16_f32 v156, v48, v49
	v_cvt_pk_bf16_f32 v157, v50, v51
	global_store_dwordx4 v[152:153], v[154:157], off offset:256
	s_branch .Lp1a_9
.Lp1f_10:
	v_add_u32_e32 v152, 0x90, v140
	v_ashrrev_i32_e32 v153, 31, v152
	v_mul_lo_u32 v162, s78, v153
	v_mul_lo_u32 v163, s79, v152
	v_mad_u64_u32 v[152:153], s[80:81], s78, v152, 0
	v_add3_u32 v153, v153, v162, v163
	v_lshl_add_u64 v[152:153], v[152:153], 1, v[150:151]
	v_cvt_pk_bf16_f32 v154, v40, v41
	v_cvt_pk_bf16_f32 v155, v42, v43
	v_cvt_pk_bf16_f32 v156, v36, v37
	v_cvt_pk_bf16_f32 v157, v38, v39
	global_store_dwordx4 v[152:153], v[154:157], off
	s_branch .Lp1a_10
.Lp1f_11:
	v_cvt_pk_bf16_f32 v154, v44, v45
	v_cvt_pk_bf16_f32 v155, v46, v47
	v_cvt_pk_bf16_f32 v156, v32, v33
	v_cvt_pk_bf16_f32 v157, v34, v35
	global_store_dwordx4 v[152:153], v[154:157], off offset:256
	s_branch .Lp1a_11
.Lp1f_12:
	v_add_u32_e32 v152, 0xa0, v140
	v_ashrrev_i32_e32 v153, 31, v152
	v_mul_lo_u32 v162, s78, v153
	v_mul_lo_u32 v163, s79, v152
	v_mad_u64_u32 v[152:153], s[80:81], s78, v152, 0
	v_add3_u32 v153, v153, v162, v163
	v_lshl_add_u64 v[152:153], v[152:153], 1, v[150:151]
	v_cvt_pk_bf16_f32 v154, v24, v25
	v_cvt_pk_bf16_f32 v155, v26, v27
	v_cvt_pk_bf16_f32 v156, v20, v21
	v_cvt_pk_bf16_f32 v157, v22, v23
	global_store_dwordx4 v[152:153], v[154:157], off
	s_branch .Lp1a_12
.Lp1f_13:
	v_cvt_pk_bf16_f32 v154, v28, v29
	v_cvt_pk_bf16_f32 v155, v30, v31
	v_cvt_pk_bf16_f32 v156, v16, v17
	v_cvt_pk_bf16_f32 v157, v18, v19
	global_store_dwordx4 v[152:153], v[154:157], off offset:256
	s_branch .Lp1a_13
.Lp1f_14:
	v_add_u32_e32 v140, 0xb0, v140
	v_ashrrev_i32_e32 v160, 31, v140
	v_mul_lo_u32 v162, s78, v160
	v_mul_lo_u32 v163, s79, v140
	v_mad_u64_u32 v[160:161], s[78:79], s78, v140, 0
	v_add3_u32 v161, v161, v162, v163
	v_lshl_add_u64 v[150:151], v[160:161], 1, v[150:151]
	v_cvt_pk_bf16_f32 v152, v8, v9
	v_cvt_pk_bf16_f32 v153, v10, v11
	v_cvt_pk_bf16_f32 v154, v4, v5
	v_cvt_pk_bf16_f32 v155, v6, v7
	global_store_dwordx4 v[150:151], v[152:155], off
	s_branch .Lp1a_14
.Lp1f_15:
	v_cvt_pk_bf16_f32 v152, v12, v13
	v_cvt_pk_bf16_f32 v153, v14, v15
	v_cvt_pk_bf16_f32 v154, v0, v1
	v_cvt_pk_bf16_f32 v155, v2, v3
	global_store_dwordx4 v[150:151], v[152:155], off offset:256
	s_branch .Lp1a_15

; __device__ __forceinline__ unsigned xb_ld(unsigned* p)              { return __hip_atomic_load(p, __ATOMIC_RELAXED, __HIP_MEMORY_SCOPE_AGENT); }
; __device__ __forceinline__ void xcd_barrier_complete(unsigned* bar, unsigned x, unsigned& nloc, unsigned& nx) {
;     const unsigned G = gridDim.x * gridDim.y * gridDim.z;
;     unsigned sum, cnt, mine, sp = 0u;
;     for (;;) {
;         sum = 0u; cnt = 0u; mine = 0u;
; #pragma unroll
;         for (unsigned j = 0; j < 16; ++j) { const unsigned c = xb_ld(&bar[XB_XCNT(j)]); sum += c; cnt += (c > 0u) ? 1u : 0u; mine = (j == x) ? c : mine; }
; __device__ __forceinline__ void xcd_barrier(const XcdBarrier& b) {
;     asm volatile("s_waitcnt vmcnt(0)" ::: "memory");
;     __syncthreads();
;     if (threadIdx.x == 0) {
;         unsigned* bar = b.bar;
;         __builtin_amdgcn_s_waitcnt(0);
;         unsigned nloc = b.st[0], nx = b.st[1];
;         if (nloc == 0u) { xcd_barrier_complete(bar, b.x, nloc, nx); b.st[0] = nloc; b.st[1] = nx; }
.LBB0_195:
	s_nop 0
	s_nop 0
	s_nop 0
	s_nop 0
	s_nop 0
	s_nop 0
	s_nop 0
	s_nop 0
	s_nop 0
	s_nop 0
	s_nop 0
	s_nop 0
	s_nop 0
	s_nop 0
	s_nop 0
	s_nop 0
	s_nop 0
	s_nop 0
	s_nop 0
	s_nop 0
	s_nop 0
	s_nop 0
	s_nop 0
	s_nop 0
	s_nop 0
	s_nop 0
	s_nop 0
	s_nop 0
	s_nop 0
	s_nop 0
	s_nop 0
	s_nop 0
	s_nop 0
	s_nop 0
	s_cmp_gt_i32 s31, 2
	s_cselect_b64 s[0:1], -1, 0
	s_and_b64 s[4:5], s[18:19], s[0:1]
	s_andn2_b64 vcc, exec, s[4:5]
	s_cbranch_vccnz .LBB0_245
	s_waitcnt vmcnt(0)
	s_waitcnt vmcnt(0) lgkmcnt(0)
	s_barrier
	s_and_saveexec_b64 s[4:5], s[8:9]
	s_cbranch_execz .LBB0_244
	s_add_i32 s6, 0, 0x25ff0
	v_mov_b32_e32 v0, s6
	s_waitcnt vmcnt(0) expcnt(0) lgkmcnt(0)
	ds_read_b32 v2, v0
	s_add_i32 s6, 0, 0x25ff4
	v_mov_b32_e32 v0, s6
	ds_read_b32 v0, v0
	s_waitcnt lgkmcnt(1)
	v_cmp_ne_u32_e32 vcc, 0, v2
	s_cbranch_vccnz .LBB0_212
	s_load_dwordx2 s[18:19], s[52:53], 0x4
	s_add_u32 s6, s28, 0x3e800200
	s_addc_u32 s7, s29, 0
	s_add_u32 s10, s28, 0x3e800400
	s_addc_u32 s11, s29, 0
	s_waitcnt lgkmcnt(0)
	s_mul_i32 s76, s18, s3
	s_add_u32 s18, s28, 0x3e800500
	s_mul_i32 s76, s76, s19
	s_addc_u32 s19, s29, 0
	s_add_u32 s20, s28, 0x3e800600
	s_addc_u32 s21, s29, 0
	s_add_u32 s22, s28, 0x3e800700
	s_addc_u32 s23, s29, 0
	s_add_u32 s24, s28, 0x3e800800
	s_addc_u32 s25, s29, 0
	s_add_u32 s42, s28, 0x3e800900
	s_addc_u32 s43, s29, 0
	s_add_u32 s44, s28, 0x3e800a00
	s_addc_u32 s45, s29, 0
	s_add_u32 s48, s28, 0x3e800b00
	s_addc_u32 s49, s29, 0
	s_add_u32 s54, s28, 0x3e800c00
	s_addc_u32 s55, s29, 0
	s_add_u32 s56, s28, 0x3e800d00
	s_addc_u32 s57, s29, 0
	s_add_u32 s58, s28, 0x3e800e00
	s_addc_u32 s59, s29, 0
	s_add_u32 s60, s28, 0x3e800f00
	s_addc_u32 s61, s29, 0
	s_add_u32 s62, s28, 0x3e801000
	s_addc_u32 s63, s29, 0
	s_add_u32 s64, s28, 0x3e801100
	s_addc_u32 s65, s29, 0
	s_add_u32 s66, s28, 0x3e801200
	s_addc_u32 s67, s29, 0
	s_add_u32 s68, s28, 0x3e801300
	s_addc_u32 s69, s29, 0
	s_mov_b32 s77, 1
	v_mov_b32_e32 v16, 0
	s_branch .LBB0_200
